# v25 + next tile's A1 half of K-tile 1 staged before the in-projection epilogue stores; third peeled wait no longer needs every store retired
# baseline (speedup 1.0000x reference)
.Lpeel_join375_2:
	s_waitcnt lgkmcnt(0)
	s_barrier
	s_setprio 1
	s_waitcnt lgkmcnt(0)
	v_mfma_f32_16x16x32_bf16 v[52:55], v[128:131], v[178:181], 0
	v_mfma_f32_16x16x32_bf16 v[48:51], v[136:139], v[178:181], 0
	v_mfma_f32_16x16x32_bf16 v[36:39], v[128:131], v[206:209], 0
	v_mfma_f32_16x16x32_bf16 v[32:35], v[136:139], v[206:209], 0
	v_mfma_f32_16x16x32_bf16 v[20:23], v[128:131], v[214:217], 0
	v_mfma_f32_16x16x32_bf16 v[16:19], v[136:139], v[214:217], 0
	v_mfma_f32_16x16x32_bf16 v[4:7], v[128:131], v[222:225], 0
	v_mfma_f32_16x16x32_bf16 v[0:3], v[136:139], v[222:225], 0
	v_mfma_f32_16x16x32_bf16 v[52:55], v[132:135], v[202:205], v[52:55]
	v_mfma_f32_16x16x32_bf16 v[48:51], v[140:143], v[202:205], v[48:51]
	v_mfma_f32_16x16x32_bf16 v[36:39], v[132:135], v[210:213], v[36:39]
	v_mfma_f32_16x16x32_bf16 v[32:35], v[140:143], v[210:213], v[32:35]
	v_mfma_f32_16x16x32_bf16 v[20:23], v[132:135], v[218:221], v[20:23]
	v_mfma_f32_16x16x32_bf16 v[16:19], v[140:143], v[218:221], v[16:19]
	v_mfma_f32_16x16x32_bf16 v[4:7], v[132:135], v[226:229], v[4:7]
	v_mfma_f32_16x16x32_bf16 v[0:3], v[140:143], v[226:229], v[0:3]
	v_mfma_f32_16x16x32_bf16 v[60:63], v[144:147], v[178:181], 0
	v_mfma_f32_16x16x32_bf16 v[56:59], v[170:173], v[178:181], 0
	v_mfma_f32_16x16x32_bf16 v[44:47], v[144:147], v[206:209], 0
	v_mfma_f32_16x16x32_bf16 v[40:43], v[170:173], v[206:209], 0
	v_mfma_f32_16x16x32_bf16 v[28:31], v[144:147], v[214:217], 0
	v_mfma_f32_16x16x32_bf16 v[24:27], v[170:173], v[214:217], 0
	v_mfma_f32_16x16x32_bf16 v[12:15], v[144:147], v[222:225], 0
	v_mfma_f32_16x16x32_bf16 v[8:11], v[170:173], v[222:225], 0
	v_mfma_f32_16x16x32_bf16 v[60:63], v[148:151], v[202:205], v[60:63]
	v_mfma_f32_16x16x32_bf16 v[56:59], v[174:177], v[202:205], v[56:59]
	v_mfma_f32_16x16x32_bf16 v[44:47], v[148:151], v[210:213], v[44:47]
	v_mfma_f32_16x16x32_bf16 v[40:43], v[174:177], v[210:213], v[40:43]
	v_mfma_f32_16x16x32_bf16 v[28:31], v[148:151], v[218:221], v[28:31]
	v_mfma_f32_16x16x32_bf16 v[24:27], v[174:177], v[218:221], v[24:27]
	v_mfma_f32_16x16x32_bf16 v[12:15], v[148:151], v[226:229], v[12:15]
	v_mfma_f32_16x16x32_bf16 v[8:11], v[174:177], v[226:229], v[8:11]
	s_setprio 0
	s_barrier
	s_add_i32 s2, 0, 0x18000
	s_add_i32 s12, 0, 0x1c000
	v_add_u32_e32 v140, s2, v195
	v_add_u32_e32 v174, s12, v195
	ds_read_b128 v[128:131], v140
	ds_read_b128 v[132:135], v140 offset:1024
	ds_read_b128 v[136:139], v140 offset:2048
	ds_read_b128 v[140:143], v140 offset:3072
	ds_read_b128 v[144:147], v174
	ds_read_b128 v[148:151], v174 offset:1024
	ds_read_b128 v[170:173], v174 offset:2048
	ds_read_b128 v[174:177], v174 offset:3072
	s_add_u32 s0, s0, s8
	s_addc_u32 s1, s1, s9
	s_mov_b32 m0, s28
	v_lshl_add_u64 v[242:243], s[0:1], 0, v[158:159]
	ds_read_b128 v[178:181], v157 offset:32768
	ds_read_b128 v[202:205], v157 offset:33792
	ds_read_b128 v[206:209], v157 offset:34816
	ds_read_b128 v[210:213], v157 offset:35840
	ds_read_b128 v[214:217], v157 offset:36864
	ds_read_b128 v[218:221], v157 offset:37888
	ds_read_b128 v[222:225], v157 offset:38912
	ds_read_b128 v[226:229], v157 offset:39936
	global_load_lds_dwordx4 v[242:243], off
	v_lshl_add_u64 v[242:243], s[0:1], 0, v[160:161]
	s_mov_b32 m0, s29
	s_nop 0
	global_load_lds_dwordx4 v[242:243], off
	s_cmp_eq_u32 s18, 1
	s_cbranch_scc1 .Lpeel_strict375_3
	s_waitcnt vmcnt(18)
	s_branch .Lpeel_join375_3

.Lpeel_join375_3:
	s_waitcnt lgkmcnt(0)
	s_barrier
	s_setprio 1
	s_waitcnt lgkmcnt(0)
	v_mfma_f32_16x16x32_bf16 v[120:123], v[128:131], v[178:181], v[120:123]
	v_mfma_f32_16x16x32_bf16 v[124:127], v[136:139], v[178:181], v[124:127]
	v_mfma_f32_16x16x32_bf16 v[100:103], v[128:131], v[206:209], v[100:103]
	v_mfma_f32_16x16x32_bf16 v[96:99], v[136:139], v[206:209], v[96:99]
	v_mfma_f32_16x16x32_bf16 v[84:87], v[128:131], v[214:217], v[84:87]
	v_mfma_f32_16x16x32_bf16 v[80:83], v[136:139], v[214:217], v[80:83]
	v_mfma_f32_16x16x32_bf16 v[68:71], v[128:131], v[222:225], v[68:71]
	v_mfma_f32_16x16x32_bf16 v[64:67], v[136:139], v[222:225], v[64:67]
	v_mfma_f32_16x16x32_bf16 v[120:123], v[132:135], v[202:205], v[120:123]
	v_mfma_f32_16x16x32_bf16 v[124:127], v[140:143], v[202:205], v[124:127]
	v_mfma_f32_16x16x32_bf16 v[100:103], v[132:135], v[210:213], v[100:103]
	v_mfma_f32_16x16x32_bf16 v[96:99], v[140:143], v[210:213], v[96:99]
	v_mfma_f32_16x16x32_bf16 v[84:87], v[132:135], v[218:221], v[84:87]
	v_mfma_f32_16x16x32_bf16 v[80:83], v[140:143], v[218:221], v[80:83]
	v_mfma_f32_16x16x32_bf16 v[68:71], v[132:135], v[226:229], v[68:71]
	v_mfma_f32_16x16x32_bf16 v[64:67], v[140:143], v[226:229], v[64:67]
	v_mfma_f32_16x16x32_bf16 v[116:119], v[144:147], v[178:181], v[116:119]
	v_mfma_f32_16x16x32_bf16 v[112:115], v[170:173], v[178:181], v[112:115]
	v_mfma_f32_16x16x32_bf16 v[108:111], v[144:147], v[206:209], v[108:111]
	v_mfma_f32_16x16x32_bf16 v[104:107], v[170:173], v[206:209], v[104:107]
	v_mfma_f32_16x16x32_bf16 v[92:95], v[144:147], v[214:217], v[92:95]
	v_mfma_f32_16x16x32_bf16 v[88:91], v[170:173], v[214:217], v[88:91]
	v_mfma_f32_16x16x32_bf16 v[76:79], v[144:147], v[222:225], v[76:79]
	v_mfma_f32_16x16x32_bf16 v[72:75], v[170:173], v[222:225], v[72:75]
	v_mfma_f32_16x16x32_bf16 v[116:119], v[148:151], v[202:205], v[116:119]
	v_mfma_f32_16x16x32_bf16 v[112:115], v[174:177], v[202:205], v[112:115]
	v_mfma_f32_16x16x32_bf16 v[108:111], v[148:151], v[210:213], v[108:111]
	v_mfma_f32_16x16x32_bf16 v[104:107], v[174:177], v[210:213], v[104:107]
	v_mfma_f32_16x16x32_bf16 v[92:95], v[148:151], v[218:221], v[92:95]
	v_mfma_f32_16x16x32_bf16 v[88:91], v[174:177], v[218:221], v[88:91]
	v_mfma_f32_16x16x32_bf16 v[76:79], v[148:151], v[226:229], v[76:79]
	v_mfma_f32_16x16x32_bf16 v[72:75], v[174:177], v[226:229], v[72:75]
	s_setprio 0
	s_barrier
	s_add_i32 s0, s2, s17
	v_lshl_add_u64 v[230:231], v[230:231], 0, s[36:37]
	s_mov_b32 m0, s0
	ds_read_b128 v[178:181], v157 offset:49152
	ds_read_b128 v[202:205], v157 offset:50176
	ds_read_b128 v[206:209], v157 offset:51200
	ds_read_b128 v[210:213], v157 offset:52224
	ds_read_b128 v[214:217], v157 offset:53248
	ds_read_b128 v[218:221], v157 offset:54272
	ds_read_b128 v[222:225], v157 offset:55296
	ds_read_b128 v[226:229], v157 offset:56320
	global_load_lds_dwordx4 v[230:231], off
	v_lshl_add_u64 v[230:231], v[232:233], 0, s[36:37]
	s_add_i32 m0, s0, 0x2000
	s_add_i32 s0, s12, s17
	global_load_lds_dwordx4 v[230:231], off
	v_lshl_add_u64 v[230:231], v[234:235], 0, s[36:37]
	s_mov_b32 m0, s0
	s_nop 0
	global_load_lds_dwordx4 v[230:231], off
	v_lshl_add_u64 v[230:231], v[236:237], 0, s[36:37]
	s_add_i32 m0, s0, 0x2000
	s_nop 0
	global_load_lds_dwordx4 v[230:231], off
	v_lshl_add_u64 v[230:231], v[238:239], 0, s[36:37]
	s_mov_b32 m0, s10
	s_nop 0
	global_load_lds_dwordx4 v[230:231], off
	v_lshl_add_u64 v[230:231], v[240:241], 0, s[36:37]
	s_mov_b32 m0, s11
	s_nop 0
	global_load_lds_dwordx4 v[230:231], off
	s_waitcnt vmcnt(10)
	s_waitcnt lgkmcnt(0)
	s_barrier
	s_setprio 1
	s_waitcnt lgkmcnt(0)
	v_mfma_f32_16x16x32_bf16 v[52:55], v[128:131], v[178:181], v[52:55]
	v_mfma_f32_16x16x32_bf16 v[48:51], v[136:139], v[178:181], v[48:51]
	v_mfma_f32_16x16x32_bf16 v[36:39], v[128:131], v[206:209], v[36:39]
	v_mfma_f32_16x16x32_bf16 v[32:35], v[136:139], v[206:209], v[32:35]
	v_mfma_f32_16x16x32_bf16 v[20:23], v[128:131], v[214:217], v[20:23]
	v_mfma_f32_16x16x32_bf16 v[16:19], v[136:139], v[214:217], v[16:19]
	v_mfma_f32_16x16x32_bf16 v[4:7], v[128:131], v[222:225], v[4:7]
	v_mfma_f32_16x16x32_bf16 v[0:3], v[136:139], v[222:225], v[0:3]
	v_mfma_f32_16x16x32_bf16 v[52:55], v[132:135], v[202:205], v[52:55]
	v_mfma_f32_16x16x32_bf16 v[48:51], v[140:143], v[202:205], v[48:51]
	v_mfma_f32_16x16x32_bf16 v[36:39], v[132:135], v[210:213], v[36:39]
	v_mfma_f32_16x16x32_bf16 v[32:35], v[140:143], v[210:213], v[32:35]
	v_mfma_f32_16x16x32_bf16 v[20:23], v[132:135], v[218:221], v[20:23]
	v_mfma_f32_16x16x32_bf16 v[16:19], v[140:143], v[218:221], v[16:19]
	v_mfma_f32_16x16x32_bf16 v[4:7], v[132:135], v[226:229], v[4:7]
	v_mfma_f32_16x16x32_bf16 v[0:3], v[140:143], v[226:229], v[0:3]
	v_mfma_f32_16x16x32_bf16 v[60:63], v[144:147], v[178:181], v[60:63]
	v_mfma_f32_16x16x32_bf16 v[56:59], v[170:173], v[178:181], v[56:59]
	v_mfma_f32_16x16x32_bf16 v[44:47], v[144:147], v[206:209], v[44:47]
	v_mfma_f32_16x16x32_bf16 v[40:43], v[170:173], v[206:209], v[40:43]
	v_mfma_f32_16x16x32_bf16 v[28:31], v[144:147], v[214:217], v[28:31]
	v_mfma_f32_16x16x32_bf16 v[24:27], v[170:173], v[214:217], v[24:27]
	v_mfma_f32_16x16x32_bf16 v[12:15], v[144:147], v[222:225], v[12:15]
	v_mfma_f32_16x16x32_bf16 v[8:11], v[170:173], v[222:225], v[8:11]
	v_mfma_f32_16x16x32_bf16 v[60:63], v[148:151], v[202:205], v[60:63]
	v_mfma_f32_16x16x32_bf16 v[56:59], v[174:177], v[202:205], v[56:59]
	v_mfma_f32_16x16x32_bf16 v[44:47], v[148:151], v[210:213], v[44:47]
	v_mfma_f32_16x16x32_bf16 v[40:43], v[174:177], v[210:213], v[40:43]
	v_mfma_f32_16x16x32_bf16 v[28:31], v[148:151], v[218:221], v[28:31]
	v_mfma_f32_16x16x32_bf16 v[24:27], v[174:177], v[218:221], v[24:27]
	v_mfma_f32_16x16x32_bf16 v[12:15], v[148:151], v[226:229], v[12:15]
	v_mfma_f32_16x16x32_bf16 v[8:11], v[174:177], v[226:229], v[8:11]
	s_setprio 0
	s_barrier
	s_add_u32 s42, s42, 0x100
	s_addc_u32 s43, s43, 0
	s_add_u32 s46, s46, 0x100
	s_addc_u32 s47, s47, 0
	s_cmp_ge_u32 s97, s31
	s_mov_b32 s0, s97
